# kv-split attention loop rescheduled: MFMA issued first in every gap, LDS reads and address math behind it, K/V LDS-DMA issue spread into MFMA gaps; prologue counted wait
# speedup vs baseline: 1.0291x; 1.0013x over previous
; template<int MODE,int THRL,bool NOMAX> __device__ __forceinline__ void attn_unit(const bf16*Qs,const bf16*__restrict__ Ks,const bf16*__restrict__ Vs,bf16*Os,int S,int q0,float sink2,float slope2,float*ssq,char*shm,int tid_in){
;   int tid_=tid_in; asm volatile("":"+v"(tid_)); const int tid=tid_,lane=tid&63,r32=lane&31,hi=lane>>5; const int wid=__builtin_amdgcn_readfirstlane(tid>>6);
;   constexpr bool LSM = NOMAX && (false);
;   int kt0=0,kend=S/KVBLK;
;   if(MODE==1){ kt0=(q0>=128?(q0-128):0)/KVBLK; const int ke=q0+QB+128; kend=(ke<S?ke:S)/KVBLK; }
;   const bf16*Qw=Qs+(long)(q0+wid*QBLK)*PITCH;
;   const bf16*Kh=Ks+(long)kt0*KVBLK*PITCH,*Vh=Vs+(long)kt0*KVBLK*PITCH;
;   const unsigned lds0=(unsigned)(uintptr_t)shm;
;   float*wsf=(float*)(shm+LDS_WS)+wid*64;
;   const bf16*ksrc=Kh+(long)lane*PITCH+wid*8;
;   const bf16*vsrc=Vh+(long)(16*(wid&3)+(lane>>2))*PITCH+(wid>>2)*32+(lane&3)*8;
;   const unsigned kdst=lds0+LDS_K+wid*1024, vdst=lds0+LDS_V+wid*1024;
;     ...
;   const int vb0=(int)(lds0+LDS_V)+((lane>>4)&1)*32+(lane&3)*8+(4*hi+((lane&15)>>2))*64;
;   const char*Kbase=shm+LDS_K; bf16x8 kf[8];
;   const lds_cptr shm3=(lds_cptr)shm; const lds_cptr kp0=shm3+LDS_K+hi*1024+r32*16; const lds_cptr vp0=shm3+LDS_V+((lane>>4)&1)*32+(lane&3)*8+(4*hi+((lane&15)>>2))*64;
;   const int NT=kend-kt0;
;   DMA_K(0,0);DMA_V(0,0);DMA_K(1,SLOTB);
;   bf16x8 qr[4];
;   #pragma unroll
;   for(int d0=0;d0<4;++d0)qr[d0]=*reinterpret_cast<const bf16x8*>(&Qw[(long)r32*PITCH+d0*16+hi*8]);
;   float mhat=0.f,l_reg=0.f;f32x16 o[2];o[0]=f32x16{};o[1]=f32x16{};f32x16 negm=f32x16{};
;   if(MODE==1){ mhat=sink2; l_reg=(hi==0)?1.f:0.f;
;     #pragma unroll
;     for(int r=0;r<16;++r)negm[r]=-sink2; }
;   if(!NOMAX)asm volatile("":"+v"(negm));
;   f32x16 lsum=f32x16{}; bf16x8 onesv;
;   #pragma unroll
;   for(int i_=0;i_<8;++i_)onesv[i_]=(short)0x3F80;
;   asm volatile("":"+v"(onesv));
;   const int qrel=wid*QBLK+r32;
;   const int qk0=q0+qrel-kt0*KVBLK-4*hi;
;     ...
;   bool resc=false;
;     ...
;   f32x16 pA0,pA1,pB0,pB1;
;   int sl_prev=0,sl_cur=0,sl_next=SLOTB,sl_n2=2*SLOTB;
;     ...
;   DMA_K(2,2*SLOTB);DMA_K(3,3*SLOTB);DMA_V(1,SLOTB);
;   WAIT_BAR(5);
;   qkt(pA0,pA1,Kbase,qr,(NOMAX?f32x16{}:negm),r32,hi);asm volatile("s_nop 15\n\ts_nop 7":"+v"(pA0),"+v"(pA1));CMASK(pA0,pA1,0);
;   START(pA0,pA1);
;   _Pragma("unroll") for(int r=0;r<16;++r)pA1[r]=__builtin_amdgcn_exp2f(pA1[r]);
;   WAIT_BAR(2);
.LBB0_549:
	s_and_b64 vcc, exec, s[4:5]
	s_cbranch_vccz .LBB0_389
	s_waitcnt lgkmcnt(0)
	v_readfirstlane_b32 s31, v251
	v_and_b32_e32 v129, 63, v251
	v_and_b32_e32 v0, 31, v251
	s_lshr_b32 s30, s31, 6
	s_and_b32 s5, s30, 3
	s_lshr_b32 s57, s30, 2
	s_lshl_b32 s4, s5, 6
	s_add_i32 s4, s4, s51
	s_lshr_b32 s40, s50, 6
	v_mul_u32_u24_e32 v214, 0xc00, v129
	s_lshl_b32 s10, s30, 4
	v_add_u32_e32 v214, s10, v214
	v_lshrrev_b32_e32 v215, 2, v129
	s_lshl_b32 s10, s5, 4
	v_add_u32_e32 v215, s10, v215
	v_mul_u32_u24_e32 v215, 0xc00, v215
	v_and_b32_e32 v217, 3, v129
	v_lshlrev_b32_e32 v217, 4, v217
	s_lshl_b32 s10, s57, 6
	v_add3_u32 v215, v215, v217, s10
	s_add_u32 s28, s28, 0x400
	s_addc_u32 s29, s29, 0
	s_add_u32 s36, s28, 0x100
	s_addc_u32 s37, s29, 0
	s_lshl_b32 s38, s30, 10
	s_add_i32 s39, s38, 0xa000
	v_lshrrev_b32_e32 v202, 5, v129
	v_lshlrev_b32_e32 v202, 10, v202
	v_lshl_add_u32 v202, v0, 4, v202
	s_lshl_b32 s10, s57, 9
	v_add_u32_e32 v202, s10, v202
	v_lshlrev_b32_e32 v217, 1, v129
	v_and_b32_e32 v217, 32, v217
	v_and_b32_e32 v126, 3, v129
	v_lshl_add_u32 v217, v126, 3, v217
	v_lshlrev_b32_e32 v126, 4, v129
	v_and_b32_e32 v126, 0xc0, v126
	v_lshrrev_b32_e32 v127, 5, v129
	v_lshl_or_b32 v126, v127, 8, v126
	s_lshl_b32 s10, s57, 11
	v_add3_u32 v217, v217, v126, s10
	s_mul_i32 s10, s4, 0xc00
	s_mul_hi_i32 s11, s4, 0xc00
	s_add_u32 s10, s52, s10
	s_addc_u32 s11, s53, s11
	s_add_u32 s14, s10, 0x18000
	s_addc_u32 s15, s11, 0
	v_mul_u32_u24_e32 v126, 0xc00, v0
	v_lshl_or_b32 v126, v127, 4, v126
	s_mov_b32 m0, s38
	s_nop 0
	global_load_lds_dwordx4 v214, s[28:29]
	s_mov_b32 m0, s39
	s_nop 0
	global_load_lds_dwordx4 v215, s[36:37]
	s_add_u32 s28, s28, 0x30000
	s_addc_u32 s29, s29, 0
	s_add_i32 m0, s38, 0x2000
	s_nop 0
	global_load_lds_dwordx4 v214, s[28:29]
	global_load_dwordx4 v[146:149], v126, s[10:11]
	global_load_dwordx4 v[150:153], v126, s[10:11] offset:32
	global_load_dwordx4 v[154:157], v126, s[10:11] offset:64
	global_load_dwordx4 v[158:161], v126, s[10:11] offset:96
	global_load_dwordx4 v[162:165], v126, s[14:15]
	global_load_dwordx4 v[166:169], v126, s[14:15] offset:32
	global_load_dwordx4 v[170:173], v126, s[14:15] offset:64
	global_load_dwordx4 v[174:177], v126, s[14:15] offset:96
	s_add_u32 s28, s28, 0x30000
	s_addc_u32 s29, s29, 0
	s_add_i32 m0, s38, 0x4000
	s_nop 0
	global_load_lds_dwordx4 v214, s[28:29]
	s_add_u32 s28, s28, 0x30000
	s_addc_u32 s29, s29, 0
	s_add_i32 m0, s38, 0x6000
	s_nop 0
	global_load_lds_dwordx4 v214, s[28:29]
	s_add_u32 s36, s36, 0x30000
	s_addc_u32 s37, s37, 0
	s_add_i32 m0, s39, 0x2000
	s_nop 0
	global_load_lds_dwordx4 v215, s[36:37]
	s_add_u32 s28, s28, 0x30000
	s_addc_u32 s29, s29, 0
	s_add_u32 s36, s36, 0x30000
	s_addc_u32 s37, s37, 0
	v_mov_b32_e32 v126, 0
	v_mov_b32_e32 v127, 0
	v_mov_b32_e32 v2, 0
	v_mov_b32_e32 v3, 0
	v_mov_b32_e32 v4, 0
	v_mov_b32_e32 v5, 0
	v_mov_b32_e32 v6, 0
	v_mov_b32_e32 v7, 0
	v_mov_b32_e32 v8, 0
	v_mov_b32_e32 v9, 0
	v_mov_b32_e32 v10, 0
	v_mov_b32_e32 v11, 0
	v_mov_b32_e32 v12, 0
	v_mov_b32_e32 v13, 0
	v_mov_b32_e32 v14, 0
	v_mov_b32_e32 v15, 0
	v_mov_b32_e32 v16, 0
	v_mov_b32_e32 v17, 0
	v_mov_b32_e32 v18, 0
	v_mov_b32_e32 v19, 0
	v_mov_b32_e32 v20, 0
	v_mov_b32_e32 v21, 0
	v_mov_b32_e32 v22, 0
	v_mov_b32_e32 v23, 0
	v_mov_b32_e32 v24, 0
	v_mov_b32_e32 v25, 0
	v_mov_b32_e32 v26, 0
	v_mov_b32_e32 v27, 0
	v_mov_b32_e32 v28, 0
	v_mov_b32_e32 v29, 0
	v_mov_b32_e32 v30, 0
	v_mov_b32_e32 v31, 0
	v_mov_b32_e32 v32, 0
	v_mov_b32_e32 v33, 0
	v_mov_b32_e32 v34, 0
	v_mov_b32_e32 v35, 0
	v_mov_b32_e32 v36, 0
	v_mov_b32_e32 v37, 0
	v_mov_b32_e32 v38, 0
	v_mov_b32_e32 v39, 0
	v_mov_b32_e32 v40, 0
	v_mov_b32_e32 v41, 0
	v_mov_b32_e32 v42, 0
	v_mov_b32_e32 v43, 0
	v_mov_b32_e32 v44, 0
	v_mov_b32_e32 v45, 0
	v_mov_b32_e32 v46, 0
	v_mov_b32_e32 v47, 0
	v_mov_b32_e32 v48, 0
	v_mov_b32_e32 v49, 0
	v_mov_b32_e32 v50, 0
	v_mov_b32_e32 v51, 0
	v_mov_b32_e32 v52, 0
	v_mov_b32_e32 v53, 0
	v_mov_b32_e32 v54, 0
	v_mov_b32_e32 v55, 0
	v_mov_b32_e32 v56, 0
	v_mov_b32_e32 v57, 0
	v_mov_b32_e32 v58, 0
	v_mov_b32_e32 v59, 0
	v_mov_b32_e32 v60, 0
	v_mov_b32_e32 v61, 0
	v_mov_b32_e32 v62, 0
	v_mov_b32_e32 v63, 0
	v_mov_b32_e32 v64, 0
	v_mov_b32_e32 v65, 0
	s_waitcnt vmcnt(3)
	s_barrier
	ds_read_b128 v[178:181], v202
	ds_read_b128 v[182:185], v202 offset:2048
	ds_read_b128 v[186:189], v202 offset:4096
	ds_read_b128 v[114:117], v202 offset:6144
	s_waitcnt lgkmcnt(0)
	v_mfma_f32_32x32x16_bf16 v[66:81], v[178:181], v[146:149], 0
	v_mfma_f32_32x32x16_bf16 v[82:97], v[178:181], v[162:165], 0
	v_mfma_f32_32x32x16_bf16 v[66:81], v[182:185], v[150:153], v[66:81]
	v_mfma_f32_32x32x16_bf16 v[82:97], v[182:185], v[166:169], v[82:97]
	v_mfma_f32_32x32x16_bf16 v[66:81], v[186:189], v[154:157], v[66:81]
	v_mfma_f32_32x32x16_bf16 v[82:97], v[186:189], v[170:173], v[82:97]
	v_mfma_f32_32x32x16_bf16 v[66:81], v[114:117], v[158:161], v[66:81]
	v_mfma_f32_32x32x16_bf16 v[82:97], v[114:117], v[174:177], v[82:97]
	s_nop 15
	s_nop 7
	v_exp_f32_e32 v66, v66
	v_exp_f32_e32 v67, v67
	v_exp_f32_e32 v68, v68
	v_exp_f32_e32 v69, v69
	v_exp_f32_e32 v70, v70
	v_exp_f32_e32 v71, v71
	v_exp_f32_e32 v72, v72
	v_exp_f32_e32 v73, v73
	v_exp_f32_e32 v74, v74
	v_exp_f32_e32 v75, v75
	v_exp_f32_e32 v76, v76
	v_exp_f32_e32 v77, v77
	v_exp_f32_e32 v78, v78
	v_exp_f32_e32 v79, v79
	v_exp_f32_e32 v80, v80
	v_exp_f32_e32 v81, v81
	v_exp_f32_e32 v82, v82
	v_exp_f32_e32 v83, v83
	v_exp_f32_e32 v84, v84
	v_exp_f32_e32 v85, v85
	v_exp_f32_e32 v86, v86
	v_exp_f32_e32 v87, v87
	v_exp_f32_e32 v88, v88
	v_exp_f32_e32 v89, v89
	v_exp_f32_e32 v90, v90
	v_exp_f32_e32 v91, v91
	v_exp_f32_e32 v92, v92
	v_exp_f32_e32 v93, v93
	v_exp_f32_e32 v94, v94
	v_exp_f32_e32 v95, v95
	v_exp_f32_e32 v96, v96
	v_exp_f32_e32 v97, v97
	s_waitcnt vmcnt(0) lgkmcnt(0)
	s_barrier
	s_add_i32 m0, s38, 0x8000
	s_nop 0
	global_load_lds_dwordx4 v214, s[28:29]
	s_add_i32 m0, s39, 0x4000
	s_nop 0
	global_load_lds_dwordx4 v215, s[36:37]
	s_add_u32 s28, s28, 0x30000
	s_addc_u32 s29, s29, 0
	s_add_u32 s36, s36, 0x30000
	s_addc_u32 s37, s37, 0
	s_mov_b32 s15, 0
	s_movk_i32 s14, 0x2000
	s_movk_i32 s44, 0x4000
	s_movk_i32 s51, 0x6000
	v_add_u32_e32 v129, s14, v202
	ds_read_b128 v[178:181], v129
	ds_read_b128 v[182:185], v129 offset:2048
	ds_read_b128 v[186:189], v129 offset:4096
	ds_read_b128 v[114:117], v129 offset:6144
	s_mov_b32 s18, 1
.Lkvs_loop:
	s_waitcnt lgkmcnt(3)
	v_mfma_f32_32x32x16_bf16 v[98:113], v[178:181], v[146:149], 0
	v_add_u32_e32 v129, s15, v217
	ds_read_b64_tr_b16 v[210:211], v129 offset:40960
	v_add_f32_e32 v0, v66, v67
	v_add_f32_e32 v0, v68, v0
	v_add_f32_e32 v0, v69, v0
	v_cvt_pk_bf16_f32 v190, v66, v67
	v_cvt_pk_bf16_f32 v191, v68, v69
	v_mfma_f32_32x32x16_bf16 v[130:145], v[178:181], v[162:165], 0
	ds_read_b64_tr_b16 v[212:213], v129 offset:41472
	v_add_f32_e32 v0, v70, v0
	v_add_f32_e32 v0, v71, v0
	v_add_f32_e32 v0, v72, v0
	v_add_f32_e32 v0, v73, v0
	v_cvt_pk_bf16_f32 v192, v70, v71
	v_cvt_pk_bf16_f32 v193, v72, v73
	s_add_i32 s10, s15, s38
	s_mov_b32 m0, s10
	s_nop 0
	global_load_lds_dwordx4 v214, s[28:29]
	s_add_u32 s28, s28, 0x30000
	s_addc_u32 s29, s29, 0
	s_waitcnt lgkmcnt(4)
	v_mfma_f32_32x32x16_bf16 v[98:113], v[182:185], v[150:153], v[98:113]
	ds_read_b64_tr_b16 v[118:119], v129 offset:45056
	v_add_f32_e32 v0, v74, v0
	v_add_f32_e32 v0, v75, v0
	v_add_f32_e32 v0, v76, v0
	v_add_f32_e32 v0, v77, v0
	v_cvt_pk_bf16_f32 v194, v74, v75
	v_cvt_pk_bf16_f32 v195, v76, v77
	v_mfma_f32_32x32x16_bf16 v[130:145], v[182:185], v[166:169], v[130:145]
	ds_read_b64_tr_b16 v[120:121], v129 offset:45568
	v_add_f32_e32 v0, v78, v0
	v_add_f32_e32 v0, v79, v0
	v_add_f32_e32 v0, v80, v0
	v_add_f32_e32 v0, v81, v0
	v_add_f32_e32 v126, v126, v0
	v_cvt_pk_bf16_f32 v196, v78, v79
	v_cvt_pk_bf16_f32 v197, v80, v81
	s_waitcnt lgkmcnt(5)
	v_mfma_f32_32x32x16_bf16 v[98:113], v[186:189], v[154:157], v[98:113]
	ds_read_b64_tr_b16 v[122:123], v129 offset:41984
	v_add_f32_e32 v0, v82, v83
	v_add_f32_e32 v0, v84, v0
	v_add_f32_e32 v0, v85, v0
	v_cvt_pk_bf16_f32 v198, v82, v83
	v_cvt_pk_bf16_f32 v199, v84, v85
	v_mfma_f32_32x32x16_bf16 v[130:145], v[186:189], v[170:173], v[130:145]
	ds_read_b64_tr_b16 v[124:125], v129 offset:42496
	v_add_f32_e32 v0, v86, v0
	v_add_f32_e32 v0, v87, v0
	v_add_f32_e32 v0, v88, v0
	v_add_f32_e32 v0, v89, v0
	v_cvt_pk_bf16_f32 v200, v86, v87
	v_cvt_pk_bf16_f32 v201, v88, v89
	s_waitcnt lgkmcnt(6)
	v_mfma_f32_32x32x16_bf16 v[98:113], v[114:117], v[158:161], v[98:113]
	ds_read_b64_tr_b16 v[218:219], v129 offset:46080
	v_add_f32_e32 v0, v90, v0
	v_add_f32_e32 v0, v91, v0
	v_add_f32_e32 v0, v92, v0
	v_add_f32_e32 v0, v93, v0
	v_cvt_pk_bf16_f32 v206, v90, v91
	v_cvt_pk_bf16_f32 v207, v92, v93
	v_mfma_f32_32x32x16_bf16 v[130:145], v[114:117], v[174:177], v[130:145]
	ds_read_b64_tr_b16 v[220:221], v129 offset:46592
	v_add_f32_e32 v0, v94, v0
	v_add_f32_e32 v0, v95, v0
	v_add_f32_e32 v0, v96, v0
	v_add_f32_e32 v0, v97, v0
	v_add_f32_e32 v127, v127, v0
	v_cvt_pk_bf16_f32 v208, v94, v95
	v_cvt_pk_bf16_f32 v209, v96, v97
	s_waitcnt lgkmcnt(6)
	v_mfma_f32_32x32x16_bf16 v[2:17], v[190:193], v[210:213], v[2:17]
	v_add_u32_e32 v129, s44, v202
	v_exp_f32_e32 v98, v98
	v_exp_f32_e32 v99, v99
	v_exp_f32_e32 v100, v100
	v_exp_f32_e32 v101, v101
	s_waitcnt lgkmcnt(4)
	v_mfma_f32_32x32x16_bf16 v[18:33], v[190:193], v[118:121], v[18:33]
	v_exp_f32_e32 v102, v102
	v_exp_f32_e32 v103, v103
	v_exp_f32_e32 v104, v104
	v_exp_f32_e32 v105, v105
	ds_read_b128 v[178:181], v129
	s_add_i32 s10, s51, s39
	s_mov_b32 m0, s10
	s_nop 0
	global_load_lds_dwordx4 v215, s[36:37]
	s_add_u32 s36, s36, 0x30000
	s_addc_u32 s37, s37, 0
	v_mfma_f32_32x32x16_bf16 v[34:49], v[198:201], v[210:213], v[34:49]
	v_exp_f32_e32 v106, v106
	v_exp_f32_e32 v107, v107
	v_exp_f32_e32 v108, v108
	v_exp_f32_e32 v109, v109
	ds_read_b128 v[182:185], v129 offset:2048
	v_mfma_f32_32x32x16_bf16 v[50:65], v[198:201], v[118:121], v[50:65]
	v_exp_f32_e32 v110, v110
	v_exp_f32_e32 v111, v111
	v_exp_f32_e32 v112, v112
	v_exp_f32_e32 v113, v113
	ds_read_b128 v[186:189], v129 offset:4096
	s_waitcnt lgkmcnt(5)
	v_mfma_f32_32x32x16_bf16 v[2:17], v[194:197], v[122:125], v[2:17]
	v_exp_f32_e32 v130, v130
	v_exp_f32_e32 v131, v131
	v_exp_f32_e32 v132, v132
	v_exp_f32_e32 v133, v133
	ds_read_b128 v[114:117], v129 offset:6144
	s_waitcnt lgkmcnt(4)
	v_mfma_f32_32x32x16_bf16 v[18:33], v[194:197], v[218:221], v[18:33]
	v_exp_f32_e32 v134, v134
	v_exp_f32_e32 v135, v135
	v_exp_f32_e32 v136, v136
	v_exp_f32_e32 v137, v137
	v_mfma_f32_32x32x16_bf16 v[34:49], v[206:209], v[122:125], v[34:49]
	v_exp_f32_e32 v138, v138
	v_exp_f32_e32 v139, v139
	v_exp_f32_e32 v140, v140
	v_exp_f32_e32 v141, v141
	v_mfma_f32_32x32x16_bf16 v[50:65], v[206:209], v[218:221], v[50:65]
	v_exp_f32_e32 v142, v142
	v_exp_f32_e32 v143, v143
	v_exp_f32_e32 v144, v144
	v_exp_f32_e32 v145, v145
	s_mov_b32 s15, s14
	s_mov_b32 s14, s44
	s_mov_b32 s44, s51
	s_add_i32 s10, s51, 0x2000
	s_cmpk_lg_u32 s51, 0x8000
	s_cselect_b32 s51, s10, 0
	s_waitcnt vmcnt(2) lgkmcnt(0)
	s_barrier
; #define WAIT_BAR(N) asm volatile("s_waitcnt vmcnt(" #N ") lgkmcnt(0)\n\ts_barrier":::"memory")
;   #define RESC() do{ if(resc){ asm volatile("s_waitcnt lgkmcnt(0)":::"memory"); \
;       _Pragma("unroll") for(int d_=0;d_<2;++d_) _Pragma("unroll") for(int r=0;r<16;++r)o[d_][r]*=wsf[crow(r,hi)]; } }while(0)
;   #define ROT() do{sl_prev=sl_cur;sl_cur=sl_next;sl_next=sl_n2;sl_n2=(sl_n2==(NSLOT-1)*SLOTB)?0:sl_n2+SLOTB;}while(0)
; template<int MODE,int THRL,bool NOMAX> __device__ __forceinline__ void attn_unit(const bf16*Qs,const bf16*__restrict__ Ks,const bf16*__restrict__ Vs,bf16*Os,int S,int q0,float sink2,float slope2,float*ssq,char*shm,int tid_in){
;     ...
;   for(;t+5<NT;t+=2){
;     STEP(pB0,pB1,pA0,pA1,t,true,true,true);     WAIT_BAR(2); RESC(); ROT();
;     STEP(pA0,pA1,pB0,pB1,t+1,true,true,true);   RESC(); ROT();
;   }
	s_waitcnt lgkmcnt(3)
	v_mfma_f32_32x32x16_bf16 v[66:81], v[178:181], v[146:149], 0
	v_add_u32_e32 v129, s15, v217
	ds_read_b64_tr_b16 v[210:211], v129 offset:40960
	v_add_f32_e32 v0, v98, v99
	v_add_f32_e32 v0, v100, v0
	v_add_f32_e32 v0, v101, v0
	v_cvt_pk_bf16_f32 v190, v98, v99
	v_cvt_pk_bf16_f32 v191, v100, v101
	v_mfma_f32_32x32x16_bf16 v[82:97], v[178:181], v[162:165], 0
	ds_read_b64_tr_b16 v[212:213], v129 offset:41472
	v_add_f32_e32 v0, v102, v0
	v_add_f32_e32 v0, v103, v0
	v_add_f32_e32 v0, v104, v0
	v_add_f32_e32 v0, v105, v0
	v_cvt_pk_bf16_f32 v192, v102, v103
	v_cvt_pk_bf16_f32 v193, v104, v105
	s_add_i32 s10, s15, s38
	s_mov_b32 m0, s10
	s_nop 0
	global_load_lds_dwordx4 v214, s[28:29]
	s_add_u32 s28, s28, 0x30000
	s_addc_u32 s29, s29, 0
	s_waitcnt lgkmcnt(4)
	v_mfma_f32_32x32x16_bf16 v[66:81], v[182:185], v[150:153], v[66:81]
	ds_read_b64_tr_b16 v[118:119], v129 offset:45056
	v_add_f32_e32 v0, v106, v0
	v_add_f32_e32 v0, v107, v0
	v_add_f32_e32 v0, v108, v0
	v_add_f32_e32 v0, v109, v0
	v_cvt_pk_bf16_f32 v194, v106, v107
	v_cvt_pk_bf16_f32 v195, v108, v109
	v_mfma_f32_32x32x16_bf16 v[82:97], v[182:185], v[166:169], v[82:97]
	ds_read_b64_tr_b16 v[120:121], v129 offset:45568
	v_add_f32_e32 v0, v110, v0
	v_add_f32_e32 v0, v111, v0
	v_add_f32_e32 v0, v112, v0
	v_add_f32_e32 v0, v113, v0
	v_add_f32_e32 v126, v126, v0
	v_cvt_pk_bf16_f32 v196, v110, v111
	v_cvt_pk_bf16_f32 v197, v112, v113
	s_waitcnt lgkmcnt(5)
	v_mfma_f32_32x32x16_bf16 v[66:81], v[186:189], v[154:157], v[66:81]
	ds_read_b64_tr_b16 v[122:123], v129 offset:41984
	v_add_f32_e32 v0, v130, v131
	v_add_f32_e32 v0, v132, v0
	v_add_f32_e32 v0, v133, v0
	v_cvt_pk_bf16_f32 v198, v130, v131
	v_cvt_pk_bf16_f32 v199, v132, v133
	v_mfma_f32_32x32x16_bf16 v[82:97], v[186:189], v[170:173], v[82:97]
	ds_read_b64_tr_b16 v[124:125], v129 offset:42496
	v_add_f32_e32 v0, v134, v0
	v_add_f32_e32 v0, v135, v0
	v_add_f32_e32 v0, v136, v0
	v_add_f32_e32 v0, v137, v0
	v_cvt_pk_bf16_f32 v200, v134, v135
	v_cvt_pk_bf16_f32 v201, v136, v137
	s_waitcnt lgkmcnt(6)
	v_mfma_f32_32x32x16_bf16 v[66:81], v[114:117], v[158:161], v[66:81]
	ds_read_b64_tr_b16 v[218:219], v129 offset:46080
	v_add_f32_e32 v0, v138, v0
	v_add_f32_e32 v0, v139, v0
	v_add_f32_e32 v0, v140, v0
	v_add_f32_e32 v0, v141, v0
	v_cvt_pk_bf16_f32 v206, v138, v139
	v_cvt_pk_bf16_f32 v207, v140, v141
	v_mfma_f32_32x32x16_bf16 v[82:97], v[114:117], v[174:177], v[82:97]
	ds_read_b64_tr_b16 v[220:221], v129 offset:46592
	v_add_f32_e32 v0, v142, v0
	v_add_f32_e32 v0, v143, v0
	v_add_f32_e32 v0, v144, v0
	v_add_f32_e32 v0, v145, v0
	v_add_f32_e32 v127, v127, v0
	v_cvt_pk_bf16_f32 v208, v142, v143
	v_cvt_pk_bf16_f32 v209, v144, v145
	s_waitcnt lgkmcnt(6)
	v_mfma_f32_32x32x16_bf16 v[2:17], v[190:193], v[210:213], v[2:17]
	v_add_u32_e32 v129, s44, v202
	v_exp_f32_e32 v66, v66
	v_exp_f32_e32 v67, v67
	v_exp_f32_e32 v68, v68
	v_exp_f32_e32 v69, v69
	s_waitcnt lgkmcnt(4)
	v_mfma_f32_32x32x16_bf16 v[18:33], v[190:193], v[118:121], v[18:33]
	v_exp_f32_e32 v70, v70
	v_exp_f32_e32 v71, v71
	v_exp_f32_e32 v72, v72
	v_exp_f32_e32 v73, v73
	ds_read_b128 v[178:181], v129
	s_add_i32 s10, s51, s39
	s_mov_b32 m0, s10
	s_nop 0
	global_load_lds_dwordx4 v215, s[36:37]
	s_add_u32 s36, s36, 0x30000
	s_addc_u32 s37, s37, 0
	v_mfma_f32_32x32x16_bf16 v[34:49], v[198:201], v[210:213], v[34:49]
	v_exp_f32_e32 v74, v74
	v_exp_f32_e32 v75, v75
	v_exp_f32_e32 v76, v76
	v_exp_f32_e32 v77, v77
	ds_read_b128 v[182:185], v129 offset:2048
	v_mfma_f32_32x32x16_bf16 v[50:65], v[198:201], v[118:121], v[50:65]
	v_exp_f32_e32 v78, v78
	v_exp_f32_e32 v79, v79
	v_exp_f32_e32 v80, v80
	v_exp_f32_e32 v81, v81
	ds_read_b128 v[186:189], v129 offset:4096
	s_waitcnt lgkmcnt(5)
	v_mfma_f32_32x32x16_bf16 v[2:17], v[194:197], v[122:125], v[2:17]
	v_exp_f32_e32 v82, v82
	v_exp_f32_e32 v83, v83
	v_exp_f32_e32 v84, v84
	v_exp_f32_e32 v85, v85
	ds_read_b128 v[114:117], v129 offset:6144
	s_waitcnt lgkmcnt(4)
	v_mfma_f32_32x32x16_bf16 v[18:33], v[194:197], v[218:221], v[18:33]
	v_exp_f32_e32 v86, v86
	v_exp_f32_e32 v87, v87
	v_exp_f32_e32 v88, v88
	v_exp_f32_e32 v89, v89
	v_mfma_f32_32x32x16_bf16 v[34:49], v[206:209], v[122:125], v[34:49]
	v_exp_f32_e32 v90, v90
	v_exp_f32_e32 v91, v91
	v_exp_f32_e32 v92, v92
	v_exp_f32_e32 v93, v93
	v_mfma_f32_32x32x16_bf16 v[50:65], v[206:209], v[218:221], v[50:65]
	v_exp_f32_e32 v94, v94
	v_exp_f32_e32 v95, v95
	v_exp_f32_e32 v96, v96
	v_exp_f32_e32 v97, v97
	s_mov_b32 s15, s14
	s_mov_b32 s14, s44
	s_mov_b32 s44, s51
	s_add_i32 s10, s51, 0x2000
	s_cmpk_lg_u32 s51, 0x8000
	s_cselect_b32 s51, s10, 0
	s_add_i32 s18, s18, 2
	s_add_i32 s10, s18, 1
	s_cmp_lt_u32 s10, s40
	s_cbranch_scc1 .Lkvs_loop
; #define WAIT_BAR(N) asm volatile("s_waitcnt vmcnt(" #N ") lgkmcnt(0)\n\ts_barrier":::"memory")
;   #define RESC() do{ if(resc){ asm volatile("s_waitcnt lgkmcnt(0)":::"memory"); \
;       _Pragma("unroll") for(int d_=0;d_<2;++d_) _Pragma("unroll") for(int r=0;r<16;++r)o[d_][r]*=wsf[crow(r,hi)]; } }while(0)
;   #define ROT() do{sl_prev=sl_cur;sl_cur=sl_next;sl_next=sl_n2;sl_n2=(sl_n2==(NSLOT-1)*SLOTB)?0:sl_n2+SLOTB;}while(0)
;   #define ENDW(tt) do{ if((tt)+4<NT){WAIT_BAR(2);} else if((tt)+2<NT){WAIT_BAR(1);} else {WAIT_BAR(0);} }while(0)
; template<int MODE,int THRL,bool NOMAX> __device__ __forceinline__ void attn_unit(const bf16*Qs,const bf16*__restrict__ Ks,const bf16*__restrict__ Vs,bf16*Os,int S,int q0,float sink2,float slope2,float*ssq,char*shm,int tid_in){
;     ...
;   for(;t+1<NT;t+=2){
;     STEP(pB0,pB1,pA0,pA1,t,(t+4<NT),(t+2<NT),(t+1<NT));       ENDW(t);   RESC(); ROT();
;     STEP(pA0,pA1,pB0,pB1,t+1,(t+5<NT),(t+3<NT),(t+2<NT));     if(t+3>=NT){WAIT_BAR(0);} RESC(); ROT();
;   }
;   STEP(pB0,pB1,pA0,pA1,NT-1,false,false,false); RESC();
	s_waitcnt lgkmcnt(3)
	v_mfma_f32_32x32x16_bf16 v[98:113], v[178:181], v[146:149], 0
	v_add_u32_e32 v129, s15, v217
	ds_read_b64_tr_b16 v[210:211], v129 offset:40960
	v_add_f32_e32 v0, v66, v67
	v_add_f32_e32 v0, v68, v0
	v_add_f32_e32 v0, v69, v0
	v_cvt_pk_bf16_f32 v190, v66, v67
	v_cvt_pk_bf16_f32 v191, v68, v69
	v_mfma_f32_32x32x16_bf16 v[130:145], v[178:181], v[162:165], 0
	ds_read_b64_tr_b16 v[212:213], v129 offset:41472
	v_add_f32_e32 v0, v70, v0
	v_add_f32_e32 v0, v71, v0
	v_add_f32_e32 v0, v72, v0
	v_add_f32_e32 v0, v73, v0
	v_cvt_pk_bf16_f32 v192, v70, v71
	v_cvt_pk_bf16_f32 v193, v72, v73
	s_add_i32 s10, s15, s38
	s_mov_b32 m0, s10
	s_nop 0
	global_load_lds_dwordx4 v214, s[28:29]
	s_add_u32 s28, s28, 0x30000
	s_addc_u32 s29, s29, 0
	s_waitcnt lgkmcnt(4)
	v_mfma_f32_32x32x16_bf16 v[98:113], v[182:185], v[150:153], v[98:113]
	ds_read_b64_tr_b16 v[118:119], v129 offset:45056
	v_add_f32_e32 v0, v74, v0
	v_add_f32_e32 v0, v75, v0
	v_add_f32_e32 v0, v76, v0
	v_add_f32_e32 v0, v77, v0
	v_cvt_pk_bf16_f32 v194, v74, v75
	v_cvt_pk_bf16_f32 v195, v76, v77
	v_mfma_f32_32x32x16_bf16 v[130:145], v[182:185], v[166:169], v[130:145]
	ds_read_b64_tr_b16 v[120:121], v129 offset:45568
	v_add_f32_e32 v0, v78, v0
	v_add_f32_e32 v0, v79, v0
	v_add_f32_e32 v0, v80, v0
	v_add_f32_e32 v0, v81, v0
	v_add_f32_e32 v126, v126, v0
	v_cvt_pk_bf16_f32 v196, v78, v79
	v_cvt_pk_bf16_f32 v197, v80, v81
	s_waitcnt lgkmcnt(5)
	v_mfma_f32_32x32x16_bf16 v[98:113], v[186:189], v[154:157], v[98:113]
	ds_read_b64_tr_b16 v[122:123], v129 offset:41984
	v_add_f32_e32 v0, v82, v83
	v_add_f32_e32 v0, v84, v0
	v_add_f32_e32 v0, v85, v0
	v_cvt_pk_bf16_f32 v198, v82, v83
	v_cvt_pk_bf16_f32 v199, v84, v85
	v_mfma_f32_32x32x16_bf16 v[130:145], v[186:189], v[170:173], v[130:145]
	ds_read_b64_tr_b16 v[124:125], v129 offset:42496
	v_add_f32_e32 v0, v86, v0
	v_add_f32_e32 v0, v87, v0
	v_add_f32_e32 v0, v88, v0
	v_add_f32_e32 v0, v89, v0
	v_cvt_pk_bf16_f32 v200, v86, v87
	v_cvt_pk_bf16_f32 v201, v88, v89
	s_waitcnt lgkmcnt(6)
	v_mfma_f32_32x32x16_bf16 v[98:113], v[114:117], v[158:161], v[98:113]
	ds_read_b64_tr_b16 v[218:219], v129 offset:46080
	v_add_f32_e32 v0, v90, v0
	v_add_f32_e32 v0, v91, v0
	v_add_f32_e32 v0, v92, v0
	v_add_f32_e32 v0, v93, v0
	v_cvt_pk_bf16_f32 v206, v90, v91
	v_cvt_pk_bf16_f32 v207, v92, v93
	v_mfma_f32_32x32x16_bf16 v[130:145], v[114:117], v[174:177], v[130:145]
	ds_read_b64_tr_b16 v[220:221], v129 offset:46592
	v_add_f32_e32 v0, v94, v0
	v_add_f32_e32 v0, v95, v0
	v_add_f32_e32 v0, v96, v0
	v_add_f32_e32 v0, v97, v0
	v_add_f32_e32 v127, v127, v0
	v_cvt_pk_bf16_f32 v208, v94, v95
	v_cvt_pk_bf16_f32 v209, v96, v97
	s_waitcnt lgkmcnt(6)
	v_mfma_f32_32x32x16_bf16 v[2:17], v[190:193], v[210:213], v[2:17]
	v_add_u32_e32 v129, s44, v202
	v_exp_f32_e32 v98, v98
	v_exp_f32_e32 v99, v99
	v_exp_f32_e32 v100, v100
	v_exp_f32_e32 v101, v101
	s_waitcnt lgkmcnt(4)
	v_mfma_f32_32x32x16_bf16 v[18:33], v[190:193], v[118:121], v[18:33]
	v_exp_f32_e32 v102, v102
	v_exp_f32_e32 v103, v103
	v_exp_f32_e32 v104, v104
	v_exp_f32_e32 v105, v105
	ds_read_b128 v[178:181], v129
	s_add_i32 s10, s51, s39
	s_mov_b32 m0, s10
	s_nop 0
	global_load_lds_dwordx4 v215, s[36:37]
	s_add_u32 s36, s36, 0x30000
	s_addc_u32 s37, s37, 0
	v_mfma_f32_32x32x16_bf16 v[34:49], v[198:201], v[210:213], v[34:49]
	v_exp_f32_e32 v106, v106
	v_exp_f32_e32 v107, v107
	v_exp_f32_e32 v108, v108
	v_exp_f32_e32 v109, v109
	ds_read_b128 v[182:185], v129 offset:2048
	v_mfma_f32_32x32x16_bf16 v[50:65], v[198:201], v[118:121], v[50:65]
	v_exp_f32_e32 v110, v110
	v_exp_f32_e32 v111, v111
	v_exp_f32_e32 v112, v112
	v_exp_f32_e32 v113, v113
	ds_read_b128 v[186:189], v129 offset:4096
	s_waitcnt lgkmcnt(5)
	v_mfma_f32_32x32x16_bf16 v[2:17], v[194:197], v[122:125], v[2:17]
	v_exp_f32_e32 v130, v130
	v_exp_f32_e32 v131, v131
	v_exp_f32_e32 v132, v132
	v_exp_f32_e32 v133, v133
	ds_read_b128 v[114:117], v129 offset:6144
	s_waitcnt lgkmcnt(4)
	v_mfma_f32_32x32x16_bf16 v[18:33], v[194:197], v[218:221], v[18:33]
	v_exp_f32_e32 v134, v134
	v_exp_f32_e32 v135, v135
	v_exp_f32_e32 v136, v136
	v_exp_f32_e32 v137, v137
	v_mfma_f32_32x32x16_bf16 v[34:49], v[206:209], v[122:125], v[34:49]
	v_exp_f32_e32 v138, v138
	v_exp_f32_e32 v139, v139
	v_exp_f32_e32 v140, v140
	v_exp_f32_e32 v141, v141
	v_mfma_f32_32x32x16_bf16 v[50:65], v[206:209], v[218:221], v[50:65]
	v_exp_f32_e32 v142, v142
	v_exp_f32_e32 v143, v143
	v_exp_f32_e32 v144, v144
	v_exp_f32_e32 v145, v145
	s_mov_b32 s15, s14
	s_mov_b32 s14, s44
	s_mov_b32 s44, s51
	s_add_i32 s10, s51, 0x2000
	s_cmpk_lg_u32 s51, 0x8000
	s_cselect_b32 s51, s10, 0
	s_waitcnt vmcnt(2) lgkmcnt(0)
	s_barrier
; #define SBAR() __builtin_amdgcn_sched_barrier(0)
;   #define PKW(P,B) cvtpk_s(P[B],P[B+1])
;   #define LSUM(k) do{ if(LSM){ lsum=__builtin_amdgcn_mfma_f32_32x32x16_bf16(PAF(k),onesv,lsum,0,0,0); SBAR(); } }while(0)
; template<int MODE,int THRL,bool NOMAX> __device__ __forceinline__ void attn_unit(const bf16*Qs,const bf16*__restrict__ Ks,const bf16*__restrict__ Vs,bf16*Os,int S,int q0,float sink2,float slope2,float*ssq,char*shm,int tid_in){
;     ...
;   { float sacc=pB0[0]+pB0[1]; _Pragma("unroll") for(int r=2;r<16;++r)sacc+=pB0[r]; _Pragma("unroll") for(int r=0;r<16;++r)sacc+=pB1[r]; l_reg+=sacc;
;     pw0=(u32x4){PKW(pB0,0),PKW(pB0,2),PKW(pB0,4),PKW(pB0,6)};pw1=(u32x4){PKW(pB0,8),PKW(pB0,10),PKW(pB0,12),PKW(pB0,14)};pw2=(u32x4){PKW(pB1,0),PKW(pB1,2),PKW(pB1,4),PKW(pB1,6)};pw3=(u32x4){PKW(pB1,8),PKW(pB1,10),PKW(pB1,12),PKW(pB1,14)};
;     SBAR(); pv(o,vb0+sl_cur,PAF(0),PAF(1),PAF(2),PAF(3)); LSUM(0); LSUM(1); LSUM(2); LSUM(3); }
	v_add_u32_e32 v129, s15, v217
	ds_read_b64_tr_b16 v[210:211], v129 offset:40960
	ds_read_b64_tr_b16 v[212:213], v129 offset:41472
	ds_read_b64_tr_b16 v[118:119], v129 offset:45056
	ds_read_b64_tr_b16 v[120:121], v129 offset:45568
	ds_read_b64_tr_b16 v[122:123], v129 offset:41984
	ds_read_b64_tr_b16 v[124:125], v129 offset:42496
	ds_read_b64_tr_b16 v[218:219], v129 offset:46080
	ds_read_b64_tr_b16 v[220:221], v129 offset:46592
	v_add_f32_e32 v0, v98, v99
	v_add_f32_e32 v0, v100, v0
	v_add_f32_e32 v0, v101, v0
	v_add_f32_e32 v0, v102, v0
	v_add_f32_e32 v0, v103, v0
	v_add_f32_e32 v0, v104, v0
	v_add_f32_e32 v0, v105, v0
	v_add_f32_e32 v0, v106, v0
	v_add_f32_e32 v0, v107, v0
	v_add_f32_e32 v0, v108, v0
	v_add_f32_e32 v0, v109, v0
	v_add_f32_e32 v0, v110, v0
	v_add_f32_e32 v0, v111, v0
	v_add_f32_e32 v0, v112, v0
	v_add_f32_e32 v0, v113, v0
	v_add_f32_e32 v126, v126, v0
	v_cvt_pk_bf16_f32 v190, v98, v99
	v_cvt_pk_bf16_f32 v191, v100, v101
	v_cvt_pk_bf16_f32 v192, v102, v103
	v_cvt_pk_bf16_f32 v193, v104, v105
	v_cvt_pk_bf16_f32 v194, v106, v107
	v_cvt_pk_bf16_f32 v195, v108, v109
	v_cvt_pk_bf16_f32 v196, v110, v111
	v_cvt_pk_bf16_f32 v197, v112, v113
	v_add_f32_e32 v0, v130, v131
	v_add_f32_e32 v0, v132, v0
	v_add_f32_e32 v0, v133, v0
	v_add_f32_e32 v0, v134, v0
	v_add_f32_e32 v0, v135, v0
	v_add_f32_e32 v0, v136, v0
	v_add_f32_e32 v0, v137, v0
	v_add_f32_e32 v0, v138, v0
	v_add_f32_e32 v0, v139, v0
	v_add_f32_e32 v0, v140, v0
	v_add_f32_e32 v0, v141, v0
	v_add_f32_e32 v0, v142, v0
	v_add_f32_e32 v0, v143, v0
	v_add_f32_e32 v0, v144, v0
	v_add_f32_e32 v0, v145, v0
	v_add_f32_e32 v127, v127, v0
	v_cvt_pk_bf16_f32 v198, v130, v131
	v_cvt_pk_bf16_f32 v199, v132, v133
	v_cvt_pk_bf16_f32 v200, v134, v135
	v_cvt_pk_bf16_f32 v201, v136, v137
	v_cvt_pk_bf16_f32 v206, v138, v139
	v_cvt_pk_bf16_f32 v207, v140, v141
	v_cvt_pk_bf16_f32 v208, v142, v143
	v_cvt_pk_bf16_f32 v209, v144, v145
	s_nop 1
	s_waitcnt lgkmcnt(6)
	v_mfma_f32_32x32x16_bf16 v[2:17], v[190:193], v[210:213], v[2:17]
	s_waitcnt lgkmcnt(4)
	v_mfma_f32_32x32x16_bf16 v[18:33], v[190:193], v[118:121], v[18:33]
	v_mfma_f32_32x32x16_bf16 v[34:49], v[198:201], v[210:213], v[34:49]
	v_mfma_f32_32x32x16_bf16 v[50:65], v[198:201], v[118:121], v[50:65]
	s_waitcnt lgkmcnt(2)
	v_mfma_f32_32x32x16_bf16 v[2:17], v[194:197], v[122:125], v[2:17]
	s_waitcnt lgkmcnt(0)
	v_mfma_f32_32x32x16_bf16 v[18:33], v[194:197], v[218:221], v[18:33]
	v_mfma_f32_32x32x16_bf16 v[34:49], v[206:209], v[122:125], v[34:49]
	v_mfma_f32_32x32x16_bf16 v[50:65], v[206:209], v[218:221], v[50:65]
	s_waitcnt vmcnt(0) lgkmcnt(0)
	s_barrier
	v_and_b32_e32 v129, 63, v251
	v_lshlrev_b32_e32 v129, 2, v129
	s_xor_b32 s10, s30, 4
	s_lshl_b32 s11, s10, 13
	v_add_u32_e32 v186, s11, v129
	s_lshl_b32 s11, s10, 8
	s_add_i32 s11, s11, 0x10000
	v_add_u32_e32 v187, s11, v129
	s_lshl_b32 s11, s30, 13
	v_add_u32_e32 v114, s11, v129
	s_lshl_b32 s11, s30, 8
	s_add_i32 s11, s11, 0x10000
	v_add_u32_e32 v115, s11, v129
	s_cmp_eq_u32 s57, 0
	s_cbranch_scc1 .Lkvs_fin0
	ds_write_b32 v186, v2 offset:0
	ds_write_b32 v186, v3 offset:256
	ds_write_b32 v186, v4 offset:512
	ds_write_b32 v186, v5 offset:768
	ds_write_b32 v186, v6 offset:1024
	ds_write_b32 v186, v7 offset:1280
	ds_write_b32 v186, v8 offset:1536
	ds_write_b32 v186, v9 offset:1792
	ds_write_b32 v186, v10 offset:2048
	ds_write_b32 v186, v11 offset:2304
	ds_write_b32 v186, v12 offset:2560
	ds_write_b32 v186, v13 offset:2816
	ds_write_b32 v186, v14 offset:3072
	ds_write_b32 v186, v15 offset:3328
	ds_write_b32 v186, v16 offset:3584
	ds_write_b32 v186, v17 offset:3840
	ds_write_b32 v186, v18 offset:4096
	ds_write_b32 v186, v19 offset:4352
	ds_write_b32 v186, v20 offset:4608
	ds_write_b32 v186, v21 offset:4864
	ds_write_b32 v186, v22 offset:5120
	ds_write_b32 v186, v23 offset:5376
	ds_write_b32 v186, v24 offset:5632
	ds_write_b32 v186, v25 offset:5888
	ds_write_b32 v186, v26 offset:6144
	ds_write_b32 v186, v27 offset:6400
	ds_write_b32 v186, v28 offset:6656
	ds_write_b32 v186, v29 offset:6912
	ds_write_b32 v186, v30 offset:7168
	ds_write_b32 v186, v31 offset:7424
	ds_write_b32 v186, v32 offset:7680
	ds_write_b32 v186, v33 offset:7936
	ds_write_b32 v187, v126
	s_waitcnt lgkmcnt(0)
	s_barrier
	ds_read_b32 v66, v114 offset:0
	ds_read_b32 v67, v114 offset:256
	ds_read_b32 v68, v114 offset:512
	ds_read_b32 v69, v114 offset:768
	ds_read_b32 v70, v114 offset:1024
	ds_read_b32 v71, v114 offset:1280
	ds_read_b32 v72, v114 offset:1536
	ds_read_b32 v73, v114 offset:1792
	ds_read_b32 v74, v114 offset:2048
	ds_read_b32 v75, v114 offset:2304
	ds_read_b32 v76, v114 offset:2560
	ds_read_b32 v77, v114 offset:2816
	ds_read_b32 v78, v114 offset:3072
	ds_read_b32 v79, v114 offset:3328
	ds_read_b32 v80, v114 offset:3584
	ds_read_b32 v81, v114 offset:3840
	ds_read_b32 v82, v114 offset:4096
	ds_read_b32 v83, v114 offset:4352
	ds_read_b32 v84, v114 offset:4608
	ds_read_b32 v85, v114 offset:4864
	ds_read_b32 v86, v114 offset:5120
	ds_read_b32 v87, v114 offset:5376
	ds_read_b32 v88, v114 offset:5632
	ds_read_b32 v89, v114 offset:5888
	ds_read_b32 v90, v114 offset:6144
	ds_read_b32 v91, v114 offset:6400
	ds_read_b32 v92, v114 offset:6656
	ds_read_b32 v93, v114 offset:6912
	ds_read_b32 v94, v114 offset:7168
	ds_read_b32 v95, v114 offset:7424
	ds_read_b32 v96, v114 offset:7680
	ds_read_b32 v97, v114 offset:7936
	ds_read_b32 v178, v115
	s_waitcnt lgkmcnt(0)
; __device__ __forceinline__ int crow(int r,int hi){return (r&3)+8*(r>>2)+4*hi;}
; template<int MODE,int THRL,bool NOMAX> __device__ __forceinline__ void attn_unit(const bf16*Qs,const bf16*__restrict__ Ks,const bf16*__restrict__ Vs,bf16*Os,int S,int q0,float sink2,float slope2,float*ssq,char*shm,int tid_in){
;     ...
;   {auto rr=__builtin_amdgcn_permlane32_swap(__float_as_uint(l_reg),__float_as_uint(l_reg),false,false);l_reg=__uint_as_float(rr[0])+__uint_as_float(rr[1]);}
;   if(hi==0)wsf[32+r32]=l_reg;asm volatile("s_waitcnt lgkmcnt(0)":::"memory");
;   float rli[16];
;   #pragma unroll
;   for(int r=0;r<16;++r)rli[r]=LSM?__builtin_amdgcn_rcpf(lsum[r]):__builtin_amdgcn_rcpf(wsf[32+crow(r,hi)]);
;     ...
;   bf16*Ow=Os+(long)(q0+wid*QBLK)*OPITCH;
;   { bf16*stg=(bf16*)(shm+LDS_OST)+wid*2048;
;     #pragma unroll
;     for(int r=0;r<16;++r){const int orow=crow(r,hi);
;       #pragma unroll
;       for(int d0=0;d0<2;++d0)stg[orow*64+d0*32+r32]=__float2bfloat16(o[d0][r]*rli[r]);}
	v_add_f32_e32 v34, v34, v66
	v_add_f32_e32 v35, v35, v67
	v_add_f32_e32 v36, v36, v68
	v_add_f32_e32 v37, v37, v69
	v_add_f32_e32 v38, v38, v70
	v_add_f32_e32 v39, v39, v71
	v_add_f32_e32 v40, v40, v72
	v_add_f32_e32 v41, v41, v73
	v_add_f32_e32 v42, v42, v74
	v_add_f32_e32 v43, v43, v75
	v_add_f32_e32 v44, v44, v76
	v_add_f32_e32 v45, v45, v77
	v_add_f32_e32 v46, v46, v78
	v_add_f32_e32 v47, v47, v79
	v_add_f32_e32 v48, v48, v80
	v_add_f32_e32 v49, v49, v81
	v_add_f32_e32 v50, v50, v82
	v_add_f32_e32 v51, v51, v83
	v_add_f32_e32 v52, v52, v84
	v_add_f32_e32 v53, v53, v85
	v_add_f32_e32 v54, v54, v86
	v_add_f32_e32 v55, v55, v87
	v_add_f32_e32 v56, v56, v88
	v_add_f32_e32 v57, v57, v89
	v_add_f32_e32 v58, v58, v90
	v_add_f32_e32 v59, v59, v91
	v_add_f32_e32 v60, v60, v92
	v_add_f32_e32 v61, v61, v93
	v_add_f32_e32 v62, v62, v94
	v_add_f32_e32 v63, v63, v95
	v_add_f32_e32 v64, v64, v96
	v_add_f32_e32 v65, v65, v97
	v_add_f32_e32 v127, v127, v178
	v_and_b32_e32 v66, 31, v251
	v_and_b32_e32 v67, 63, v251
	v_lshrrev_b32_e32 v67, 5, v67
	s_lshl_b32 s10, s30, 8
	s_add_i32 s10, s10, 0x14000
	s_lshl_b32 s11, s30, 12
	s_add_i32 s11, s11, 0x14800
	v_and_b32_e32 v74, 63, v251
	v_lshrrev_b32_e32 v75, 3, v74
	v_and_b32_e32 v74, 7, v74
	v_lshlrev_b32_e32 v76, 4, v74
	v_lshl_add_u32 v76, v75, 7, v76
	v_add_u32_e32 v76, s11, v76
	v_lshlrev_b32_e32 v69, 9, v67
	v_lshl_add_u32 v69, v66, 1, v69
	v_add_u32_e32 v69, s11, v69
	v_lshl_add_u32 v68, v66, 2, s10
	v_mov_b32_e32 v70, v127
	s_nop 1
	v_permlane32_swap_b32_e32 v127, v70
	s_nop 1
	v_add_f32_e32 v70, v127, v70
	ds_write_b32 v68, v70 offset:128
	v_lshl_add_u32 v71, v67, 4, s10
	s_waitcnt lgkmcnt(0)
	ds_read_b128 v[82:85], v71 offset:128
	ds_read_b128 v[86:89], v71 offset:160
	ds_read_b128 v[90:93], v71 offset:192
	ds_read_b128 v[94:97], v71 offset:224
	s_waitcnt lgkmcnt(0)
	v_rcp_f32_e32 v82, v82
	v_rcp_f32_e32 v83, v83
	v_rcp_f32_e32 v84, v84
	v_rcp_f32_e32 v85, v85
	v_rcp_f32_e32 v86, v86
	v_rcp_f32_e32 v87, v87
	v_rcp_f32_e32 v88, v88
	v_rcp_f32_e32 v89, v89
	v_rcp_f32_e32 v90, v90
	v_rcp_f32_e32 v91, v91
	v_rcp_f32_e32 v92, v92
	v_rcp_f32_e32 v93, v93
	v_rcp_f32_e32 v94, v94
	v_rcp_f32_e32 v95, v95
	v_rcp_f32_e32 v96, v96
	v_rcp_f32_e32 v97, v97
	s_nop 0
	v_mul_f32_e32 v72, v34, v82
	v_cvt_pk_bf16_f32 v72, v72, v72
	ds_write_b16 v69, v72 offset:0
	v_mul_f32_e32 v73, v50, v82
	v_cvt_pk_bf16_f32 v73, v73, v73
	ds_write_b16 v69, v73 offset:64
	v_mul_f32_e32 v72, v35, v83
	v_cvt_pk_bf16_f32 v72, v72, v72
	ds_write_b16 v69, v72 offset:128
	v_mul_f32_e32 v73, v51, v83
	v_cvt_pk_bf16_f32 v73, v73, v73
	ds_write_b16 v69, v73 offset:192
	v_mul_f32_e32 v72, v36, v84
	v_cvt_pk_bf16_f32 v72, v72, v72
	ds_write_b16 v69, v72 offset:256
	v_mul_f32_e32 v73, v52, v84
	v_cvt_pk_bf16_f32 v73, v73, v73
	ds_write_b16 v69, v73 offset:320
	v_mul_f32_e32 v72, v37, v85
	v_cvt_pk_bf16_f32 v72, v72, v72
	ds_write_b16 v69, v72 offset:384
	v_mul_f32_e32 v73, v53, v85
	v_cvt_pk_bf16_f32 v73, v73, v73
	ds_write_b16 v69, v73 offset:448
	v_mul_f32_e32 v72, v38, v86
	v_cvt_pk_bf16_f32 v72, v72, v72
	ds_write_b16 v69, v72 offset:1024
	v_mul_f32_e32 v73, v54, v86
	v_cvt_pk_bf16_f32 v73, v73, v73
	ds_write_b16 v69, v73 offset:1088
	v_mul_f32_e32 v72, v39, v87
	v_cvt_pk_bf16_f32 v72, v72, v72
	ds_write_b16 v69, v72 offset:1152
	v_mul_f32_e32 v73, v55, v87
	v_cvt_pk_bf16_f32 v73, v73, v73
	ds_write_b16 v69, v73 offset:1216
	v_mul_f32_e32 v72, v40, v88
	v_cvt_pk_bf16_f32 v72, v72, v72
	ds_write_b16 v69, v72 offset:1280
	v_mul_f32_e32 v73, v56, v88
	v_cvt_pk_bf16_f32 v73, v73, v73
	ds_write_b16 v69, v73 offset:1344
	v_mul_f32_e32 v72, v41, v89
	v_cvt_pk_bf16_f32 v72, v72, v72
	ds_write_b16 v69, v72 offset:1408
	v_mul_f32_e32 v73, v57, v89
	v_cvt_pk_bf16_f32 v73, v73, v73
	ds_write_b16 v69, v73 offset:1472
	v_mul_f32_e32 v72, v42, v90
	v_cvt_pk_bf16_f32 v72, v72, v72
	ds_write_b16 v69, v72 offset:2048
	v_mul_f32_e32 v73, v58, v90
	v_cvt_pk_bf16_f32 v73, v73, v73
	ds_write_b16 v69, v73 offset:2112
	v_mul_f32_e32 v72, v43, v91
	v_cvt_pk_bf16_f32 v72, v72, v72
	ds_write_b16 v69, v72 offset:2176
	v_mul_f32_e32 v73, v59, v91
	v_cvt_pk_bf16_f32 v73, v73, v73
	ds_write_b16 v69, v73 offset:2240
	v_mul_f32_e32 v72, v44, v92
	v_cvt_pk_bf16_f32 v72, v72, v72
	ds_write_b16 v69, v72 offset:2304
	v_mul_f32_e32 v73, v60, v92
	v_cvt_pk_bf16_f32 v73, v73, v73
	ds_write_b16 v69, v73 offset:2368
	v_mul_f32_e32 v72, v45, v93
	v_cvt_pk_bf16_f32 v72, v72, v72
	ds_write_b16 v69, v72 offset:2432
	v_mul_f32_e32 v73, v61, v93
	v_cvt_pk_bf16_f32 v73, v73, v73
	ds_write_b16 v69, v73 offset:2496
	v_mul_f32_e32 v72, v46, v94
	v_cvt_pk_bf16_f32 v72, v72, v72
	ds_write_b16 v69, v72 offset:3072
	v_mul_f32_e32 v73, v62, v94
	v_cvt_pk_bf16_f32 v73, v73, v73
	ds_write_b16 v69, v73 offset:3136
	v_mul_f32_e32 v72, v47, v95
	v_cvt_pk_bf16_f32 v72, v72, v72
	ds_write_b16 v69, v72 offset:3200
	v_mul_f32_e32 v73, v63, v95
	v_cvt_pk_bf16_f32 v73, v73, v73
	ds_write_b16 v69, v73 offset:3264
	v_mul_f32_e32 v72, v48, v96
	v_cvt_pk_bf16_f32 v72, v72, v72
	ds_write_b16 v69, v72 offset:3328
	v_mul_f32_e32 v73, v64, v96
	v_cvt_pk_bf16_f32 v73, v73, v73
	ds_write_b16 v69, v73 offset:3392
	v_mul_f32_e32 v72, v49, v97
	v_cvt_pk_bf16_f32 v72, v72, v72
	ds_write_b16 v69, v72 offset:3456
	v_mul_f32_e32 v73, v65, v97
	v_cvt_pk_bf16_f32 v73, v73, v73
	ds_write_b16 v69, v73 offset:3520
	s_add_i32 s14, s4, 32
	s_mul_i32 s18, s14, 0x800
	s_mul_hi_i32 s19, s14, 0x800
	s_add_u32 s18, s48, s18
	s_addc_u32 s19, s49, s19
	s_mul_i32 s44, s14, 64
	s_mul_hi_i32 s45, s14, 64
	s_add_u32 s44, s26, s44
	s_addc_u32 s45, s27, s45
	v_lshlrev_b32_e32 v78, 11, v75
	v_lshl_add_u32 v78, v74, 4, v78
	v_lshlrev_b32_e32 v77, 6, v75
	v_cmp_eq_u32_e32 vcc, 0, v74
	s_waitcnt lgkmcnt(0)
; #define lane ({ int l_ = (int)__builtin_amdgcn_mbcnt_hi(~0u, __builtin_amdgcn_mbcnt_lo(~0u, 0u)); asm volatile("" : "+v"(l_)); l_; })
; template<int MODE,int THRL,bool NOMAX> __device__ __forceinline__ void attn_unit(const bf16*Qs,const bf16*__restrict__ Ks,const bf16*__restrict__ Vs,bf16*Os,int S,int q0,float sink2,float slope2,float*ssq,char*shm,int tid_in){
;     ...
;     asm volatile("s_waitcnt lgkmcnt(0)":::"memory");
;     #pragma unroll
;     for(int i=0;i<4;++i){const int row=i*8+(lane>>3),ch=lane&7; const u32x4 v=*(const u32x4*)(stg+row*64+ch*8); ATTN_STORE16(Ow+(long)row*OPITCH+ch*8,v);
;       float sq=0.f;
;       #pragma unroll
;       for(int k=0;k<4;++k){const float a=__uint_as_float(v[k]<<16),b=__uint_as_float(v[k]&0xffff0000u); sq+=a*a+b*b;}
;       sq+=__shfl_xor(sq,1); sq+=__shfl_xor(sq,2); sq+=__shfl_xor(sq,4);
;       if(ch==0)ssq[(long)(q0+wid*QBLK+row)*16]=sq;} }
	ds_read_b128 v[98:101], v76 offset:0
	ds_read_b128 v[102:105], v76 offset:1024
	ds_read_b128 v[106:109], v76 offset:2048
	ds_read_b128 v[110:113], v76 offset:3072
	s_waitcnt lgkmcnt(3)
	global_store_dwordx4 v78, v[98:101], s[18:19] offset:0
	v_and_b32_e32 v72, 0xffff0000, v98
	v_lshlrev_b32_e32 v73, 16, v98
	v_mul_f32_e32 v72, v72, v72
	v_fmac_f32_e32 v72, v73, v73
	v_mov_b32_e32 v130, v72
	v_and_b32_e32 v72, 0xffff0000, v99
	v_lshlrev_b32_e32 v73, 16, v99
	v_mul_f32_e32 v72, v72, v72
	v_fmac_f32_e32 v72, v73, v73
	v_add_f32_e32 v130, v130, v72
	v_and_b32_e32 v72, 0xffff0000, v100
	v_lshlrev_b32_e32 v73, 16, v100
	v_mul_f32_e32 v72, v72, v72
	v_fmac_f32_e32 v72, v73, v73
	v_add_f32_e32 v130, v72, v130
	v_and_b32_e32 v72, 0xffff0000, v101
	v_lshlrev_b32_e32 v73, 16, v101
	v_mul_f32_e32 v72, v72, v72
	v_fmac_f32_e32 v72, v73, v73
	v_add_f32_e32 v130, v72, v130
	v_add_u32_e32 v78, 0x4000, v78
	s_waitcnt lgkmcnt(2)
	global_store_dwordx4 v78, v[102:105], s[18:19]
	v_and_b32_e32 v72, 0xffff0000, v102
	v_lshlrev_b32_e32 v73, 16, v102
	v_mul_f32_e32 v72, v72, v72
	v_fmac_f32_e32 v72, v73, v73
	v_mov_b32_e32 v131, v72
	v_and_b32_e32 v72, 0xffff0000, v103
	v_lshlrev_b32_e32 v73, 16, v103
	v_mul_f32_e32 v72, v72, v72
	v_fmac_f32_e32 v72, v73, v73
	v_add_f32_e32 v131, v131, v72
	v_and_b32_e32 v72, 0xffff0000, v104
	v_lshlrev_b32_e32 v73, 16, v104
	v_mul_f32_e32 v72, v72, v72
	v_fmac_f32_e32 v72, v73, v73
	v_add_f32_e32 v131, v72, v131
	v_and_b32_e32 v72, 0xffff0000, v105
	v_lshlrev_b32_e32 v73, 16, v105
	v_mul_f32_e32 v72, v72, v72
	v_fmac_f32_e32 v72, v73, v73
	v_add_f32_e32 v131, v72, v131
	v_add_u32_e32 v78, 0x4000, v78
	s_waitcnt lgkmcnt(1)
	global_store_dwordx4 v78, v[106:109], s[18:19]
	v_and_b32_e32 v72, 0xffff0000, v106
	v_lshlrev_b32_e32 v73, 16, v106
	v_mul_f32_e32 v72, v72, v72
	v_fmac_f32_e32 v72, v73, v73
	v_mov_b32_e32 v132, v72
	v_and_b32_e32 v72, 0xffff0000, v107
	v_lshlrev_b32_e32 v73, 16, v107
	v_mul_f32_e32 v72, v72, v72
	v_fmac_f32_e32 v72, v73, v73
	v_add_f32_e32 v132, v132, v72
	v_and_b32_e32 v72, 0xffff0000, v108
	v_lshlrev_b32_e32 v73, 16, v108
	v_mul_f32_e32 v72, v72, v72
	v_fmac_f32_e32 v72, v73, v73
	v_add_f32_e32 v132, v72, v132
	v_and_b32_e32 v72, 0xffff0000, v109
	v_lshlrev_b32_e32 v73, 16, v109
	v_mul_f32_e32 v72, v72, v72
	v_fmac_f32_e32 v72, v73, v73
	v_add_f32_e32 v132, v72, v132
	v_add_u32_e32 v78, 0x4000, v78
	s_waitcnt lgkmcnt(0)
	global_store_dwordx4 v78, v[110:113], s[18:19]
	v_and_b32_e32 v72, 0xffff0000, v110
	v_lshlrev_b32_e32 v73, 16, v110
	v_mul_f32_e32 v72, v72, v72
	v_fmac_f32_e32 v72, v73, v73
	v_mov_b32_e32 v133, v72
	v_and_b32_e32 v72, 0xffff0000, v111
	v_lshlrev_b32_e32 v73, 16, v111
	v_mul_f32_e32 v72, v72, v72
	v_fmac_f32_e32 v72, v73, v73
	v_add_f32_e32 v133, v133, v72
	v_and_b32_e32 v72, 0xffff0000, v112
	v_lshlrev_b32_e32 v73, 16, v112
	v_mul_f32_e32 v72, v72, v72
	v_fmac_f32_e32 v72, v73, v73
	v_add_f32_e32 v133, v72, v133
	v_and_b32_e32 v72, 0xffff0000, v113
	v_lshlrev_b32_e32 v73, 16, v113
	v_mul_f32_e32 v72, v72, v72
	v_fmac_f32_e32 v72, v73, v73
	v_add_f32_e32 v133, v72, v133
	ds_bpermute_b32 v134, v239, v130
	ds_bpermute_b32 v135, v239, v131
	ds_bpermute_b32 v136, v239, v132
	ds_bpermute_b32 v137, v239, v133
	s_waitcnt lgkmcnt(0)
	v_add_f32_e32 v130, v130, v134
	v_add_f32_e32 v131, v131, v135
	v_add_f32_e32 v132, v132, v136
	v_add_f32_e32 v133, v133, v137
	ds_bpermute_b32 v134, v240, v130
	ds_bpermute_b32 v135, v240, v131
	ds_bpermute_b32 v136, v240, v132
	ds_bpermute_b32 v137, v240, v133
	s_waitcnt lgkmcnt(0)
	v_add_f32_e32 v130, v130, v134
	v_add_f32_e32 v131, v131, v135
	v_add_f32_e32 v132, v132, v136
	v_add_f32_e32 v133, v133, v137
	ds_bpermute_b32 v134, v241, v130
	ds_bpermute_b32 v135, v241, v131
	ds_bpermute_b32 v136, v241, v132
	ds_bpermute_b32 v137, v241, v133
	s_waitcnt lgkmcnt(0)
	v_add_f32_e32 v130, v130, v134
	v_add_f32_e32 v131, v131, v135
	v_add_f32_e32 v132, v132, v136
	v_add_f32_e32 v133, v133, v137
	s_nop 3
	s_and_saveexec_b64 s[10:11], vcc
	global_store_dword v77, v130, s[44:45]
	global_store_dword v77, v131, s[44:45] offset:512
	global_store_dword v77, v132, s[44:45] offset:1024
	global_store_dword v77, v133, s[44:45] offset:1536
	s_or_b64 exec, exec, s[10:11]
	s_branch .Lkvs_done
